# sample_ssd peeled last head: A_log, D and z-gate taken from the one-head-ahead loads instead of reloading
# baseline (speedup 1.0000x reference)
; __device__ __forceinline__ void sample_ssd(const Params& p, unsigned char* smem, int job) {
;     ...
;     for (int hh = 0; hh < 16; ++hh) {
;         const int h = g * 16 + hh;
;         const float A_h = -__expf(p.in[14][h]), D_h = p.in[15][h];
;         float dtv[8], cum[8];
;         { float run = 0.f;
; #pragma unroll
;           for (int t = 0; t < 8; ++t) { dtv[t] = dts[hh * 8 + t]; run += dtv[t] * A_h; cum[t] = run; } }
;         const size_t soff = ((size_t)(b * 32 + h) * 64 + pp) * 128 + nq * 4;
;         f32x4 s0[4];
; #pragma unroll
;         for (int i = 0; i < 4; ++i) s0[i] = snext[i];
;         if (hh + 1 < 16) {
; #pragma unroll
;             for (int i = 0; i < 4; ++i) snext[i] = __builtin_nontemporal_load((const f32x4*)(p.in[3] + soff + 64 * 128 + 32 * i));
;         }
;         float cs[8];
; #pragma unroll
;         for (int t = 0; t < 8; ++t) {
;             float sum = 0.f;
; #pragma unroll
;             for (int i = 0; i < 4; ++i) { const f32x4 c4 = *(const f32x4*)(Cc + t * 128 + nq * 4 + 32 * i); sum += c4[0] * s0[i][0] + c4[1] * s0[i][1] + c4[2] * s0[i][2] + c4[3] * s0[i][3]; }
;             sum += __shfl_xor(sum, 1); sum += __shfl_xor(sum, 2); sum += __shfl_xor(sum, 4);
;             cs[t] = sum;
;         }
.LBB0_694:
	s_lshl_b32 s36, s44, 2
	v_readlane_b32 s56, v254, 59
	v_mov_b32_e32 v20, s36
	v_readlane_b32 s68, v255, 7
	v_readlane_b32 s69, v255, 8
	v_readlane_b32 s70, v255, 9
	v_readlane_b32 s71, v255, 10
	v_readlane_b32 s57, v254, 60
	v_readlane_b32 s58, v254, 61
	v_readlane_b32 s59, v254, 62
	v_mov_b32_e32 v21, v119
	v_readlane_b32 s60, v254, 63
	v_mov_b32_e32 v28, v120
	v_readlane_b32 s61, v255, 0
	v_readlane_b32 s62, v255, 1
	v_readlane_b32 s63, v255, 2
	v_readlane_b32 s64, v255, 3
	v_readlane_b32 s65, v255, 4
	v_readlane_b32 s66, v255, 5
	v_readlane_b32 s67, v255, 6
	s_nop 0
	v_mul_f32_e32 v21, 0x3fb8aa3b, v21
	v_exp_f32_e32 v29, v21
	ds_read_b128 v[24:27], v149 offset:41696
	ds_read_b128 v[20:23], v149 offset:41712
	ds_read_b128 v[30:33], v83 offset:4096
	s_waitcnt lgkmcnt(2)
	v_fma_f32 v55, -v29, v24, 0
	v_fma_f32 v54, -v29, v25, v55
	v_fma_f32 v53, -v29, v26, v54
	v_fma_f32 v52, -v29, v27, v53
	s_waitcnt lgkmcnt(1)
	v_fma_f32 v43, -v29, v20, v52
	v_fma_f32 v42, -v29, v21, v43
	v_fma_f32 v40, -v29, v22, v42
	v_fma_f32 v41, -v29, v23, v40
	s_waitcnt lgkmcnt(0)
	v_mul_f32_e32 v29, v17, v31
	v_fmac_f32_e32 v29, v16, v30
	v_fmac_f32_e32 v29, v18, v32
	v_fmac_f32_e32 v29, v19, v33
	ds_read_b128 v[30:33], v83 offset:4224
	v_add_f32_e32 v29, 0, v29
	s_waitcnt lgkmcnt(0)
	v_mul_f32_e32 v31, v13, v31
	v_fmac_f32_e32 v31, v12, v30
	v_fmac_f32_e32 v31, v14, v32
	v_fmac_f32_e32 v31, v15, v33
	v_add_f32_e32 v29, v29, v31
	ds_read_b128 v[30:33], v83 offset:4352
	s_waitcnt lgkmcnt(0)
	v_mul_f32_e32 v31, v9, v31
	v_fmac_f32_e32 v31, v8, v30
	v_fmac_f32_e32 v31, v10, v32
	v_fmac_f32_e32 v31, v11, v33
	v_add_f32_e32 v29, v29, v31
	ds_read_b128 v[30:33], v83 offset:4480
	s_waitcnt lgkmcnt(0)
	v_mul_f32_e32 v31, v5, v31
	v_fmac_f32_e32 v31, v4, v30
	v_fmac_f32_e32 v31, v6, v32
	v_fmac_f32_e32 v31, v7, v33
	v_add_f32_e32 v29, v29, v31
	ds_bpermute_b32 v30, v82, v29
	s_waitcnt lgkmcnt(0)
	v_add_f32_e32 v29, v29, v30
	ds_bpermute_b32 v30, v81, v29
	s_waitcnt lgkmcnt(0)
	v_add_f32_e32 v29, v29, v30
	ds_read_b128 v[30:33], v83 offset:4608
	ds_bpermute_b32 v35, v80, v29
	s_waitcnt lgkmcnt(1)
	v_mul_f32_e32 v31, v17, v31
	v_fmac_f32_e32 v31, v16, v30
	v_fmac_f32_e32 v31, v18, v32
	v_fmac_f32_e32 v31, v19, v33
	v_add_f32_e32 v34, 0, v31
	ds_read_b128 v[30:33], v83 offset:4736
	s_waitcnt lgkmcnt(0)
	v_mul_f32_e32 v31, v13, v31
	v_fmac_f32_e32 v31, v12, v30
	v_fmac_f32_e32 v31, v14, v32
	v_fmac_f32_e32 v31, v15, v33
	v_add_f32_e32 v34, v34, v31
	ds_read_b128 v[30:33], v83 offset:4864
	s_waitcnt lgkmcnt(0)
	v_mul_f32_e32 v31, v9, v31
	v_fmac_f32_e32 v31, v8, v30
	v_fmac_f32_e32 v31, v10, v32
	v_fmac_f32_e32 v31, v11, v33
	v_add_f32_e32 v34, v34, v31
	ds_read_b128 v[30:33], v83 offset:4992
	s_waitcnt lgkmcnt(0)
	v_mul_f32_e32 v31, v5, v31
	v_fmac_f32_e32 v31, v4, v30
	v_fmac_f32_e32 v31, v6, v32
	v_fmac_f32_e32 v31, v7, v33
	v_add_f32_e32 v30, v34, v31
	ds_bpermute_b32 v31, v82, v30
	s_waitcnt lgkmcnt(0)
	v_add_f32_e32 v30, v30, v31
	ds_bpermute_b32 v31, v81, v30
	s_waitcnt lgkmcnt(0)
	v_add_f32_e32 v56, v30, v31
	ds_read_b128 v[30:33], v83 offset:5120
	ds_bpermute_b32 v57, v80, v56
	s_waitcnt lgkmcnt(1)
	v_mul_f32_e32 v31, v17, v31
	v_fmac_f32_e32 v31, v16, v30
	v_fmac_f32_e32 v31, v18, v32
	v_fmac_f32_e32 v31, v19, v33
	v_add_f32_e32 v34, 0, v31
	ds_read_b128 v[30:33], v83 offset:5248
	s_waitcnt lgkmcnt(0)
	v_mul_f32_e32 v31, v13, v31
	v_fmac_f32_e32 v31, v12, v30
	v_fmac_f32_e32 v31, v14, v32
	v_fmac_f32_e32 v31, v15, v33
	v_add_f32_e32 v34, v34, v31
	ds_read_b128 v[30:33], v83 offset:5376
	s_waitcnt lgkmcnt(0)
	v_mul_f32_e32 v31, v9, v31
	v_fmac_f32_e32 v31, v8, v30
	v_fmac_f32_e32 v31, v10, v32
	v_fmac_f32_e32 v31, v11, v33
	v_add_f32_e32 v34, v34, v31
	ds_read_b128 v[30:33], v83 offset:5504
	s_waitcnt lgkmcnt(0)
	v_mul_f32_e32 v31, v5, v31
	v_fmac_f32_e32 v31, v4, v30
	v_fmac_f32_e32 v31, v6, v32
	v_fmac_f32_e32 v31, v7, v33
	v_add_f32_e32 v30, v34, v31
	ds_bpermute_b32 v31, v82, v30
	s_waitcnt lgkmcnt(0)
	v_add_f32_e32 v30, v30, v31
	ds_bpermute_b32 v31, v81, v30
	s_waitcnt lgkmcnt(0)
	v_add_f32_e32 v58, v30, v31
	ds_read_b128 v[30:33], v83 offset:5632
	ds_bpermute_b32 v59, v80, v58
	s_waitcnt lgkmcnt(1)
	v_mul_f32_e32 v31, v17, v31
	v_fmac_f32_e32 v31, v16, v30
	v_fmac_f32_e32 v31, v18, v32
	v_fmac_f32_e32 v31, v19, v33
	v_add_f32_e32 v34, 0, v31
	ds_read_b128 v[30:33], v83 offset:5760
	s_waitcnt lgkmcnt(0)
	v_mul_f32_e32 v31, v13, v31
	v_fmac_f32_e32 v31, v12, v30
	v_fmac_f32_e32 v31, v14, v32
	v_fmac_f32_e32 v31, v15, v33
	v_add_f32_e32 v34, v34, v31
	ds_read_b128 v[30:33], v83 offset:5888
	s_waitcnt lgkmcnt(0)
	v_mul_f32_e32 v31, v9, v31
	v_fmac_f32_e32 v31, v8, v30
	v_fmac_f32_e32 v31, v10, v32
	v_fmac_f32_e32 v31, v11, v33
	v_add_f32_e32 v34, v34, v31
	ds_read_b128 v[30:33], v83 offset:6016
	s_waitcnt lgkmcnt(0)
	v_mul_f32_e32 v31, v5, v31
	v_fmac_f32_e32 v31, v4, v30
	v_fmac_f32_e32 v31, v6, v32
	v_fmac_f32_e32 v31, v7, v33
	v_add_f32_e32 v30, v34, v31
	ds_bpermute_b32 v31, v82, v30
	s_waitcnt lgkmcnt(0)
; __device__ __forceinline__ void sample_ssd(const Params& p, unsigned char* smem, int job) {
;     ...
;         for (int t = 0; t < 8; ++t) {
;             float sum = 0.f;
; #pragma unroll
;             for (int i = 0; i < 4; ++i) { const f32x4 c4 = *(const f32x4*)(Cc + t * 128 + nq * 4 + 32 * i); sum += c4[0] * s0[i][0] + c4[1] * s0[i][1] + c4[2] * s0[i][2] + c4[3] * s0[i][3]; }
;             sum += __shfl_xor(sum, 1); sum += __shfl_xor(sum, 2); sum += __shfl_xor(sum, 4);
;             cs[t] = sum;
;         }
;         float ycs = 0.f, ct = 0.f;
; #pragma unroll
;         for (int t = 0; t < 8; ++t) { ycs = (nq == t) ? cs[t] : ycs; ct = (nq == t) ? cum[t] : ct; }
;         float y = __expf(ct) * ycs, xt = 0.f;
; #pragma unroll
;         for (int s = 0; s < 8; ++s) {
;             const float xs = xall[s * 1024 + hh * 64 + pp];
;             const float term = (s <= nq) ? G[nq * 8 + s] * __expf(ct - cum[s]) * dtv[s] * xs : 0.f;
	v_add_f32_e32 v30, v30, v31
	ds_bpermute_b32 v31, v81, v30
	s_waitcnt lgkmcnt(0)
	v_add_f32_e32 v60, v30, v31
	ds_read_b128 v[30:33], v83 offset:6144
	ds_bpermute_b32 v61, v80, v60
	s_waitcnt lgkmcnt(1)
	v_mul_f32_e32 v31, v17, v31
	v_fmac_f32_e32 v31, v16, v30
	v_fmac_f32_e32 v31, v18, v32
	v_fmac_f32_e32 v31, v19, v33
	v_add_f32_e32 v34, 0, v31
	ds_read_b128 v[30:33], v83 offset:6272
	s_waitcnt lgkmcnt(0)
	v_mul_f32_e32 v31, v13, v31
	v_fmac_f32_e32 v31, v12, v30
	v_fmac_f32_e32 v31, v14, v32
	v_fmac_f32_e32 v31, v15, v33
	v_add_f32_e32 v34, v34, v31
	ds_read_b128 v[30:33], v83 offset:6400
	s_waitcnt lgkmcnt(0)
	v_mul_f32_e32 v31, v9, v31
	v_fmac_f32_e32 v31, v8, v30
	v_fmac_f32_e32 v31, v10, v32
	v_fmac_f32_e32 v31, v11, v33
	v_add_f32_e32 v34, v34, v31
	ds_read_b128 v[30:33], v83 offset:6528
	s_waitcnt lgkmcnt(0)
	v_mul_f32_e32 v31, v5, v31
	v_fmac_f32_e32 v31, v4, v30
	v_fmac_f32_e32 v31, v6, v32
	v_fmac_f32_e32 v31, v7, v33
	v_add_f32_e32 v30, v34, v31
	ds_bpermute_b32 v31, v82, v30
	s_waitcnt lgkmcnt(0)
	v_add_f32_e32 v30, v30, v31
	ds_bpermute_b32 v31, v81, v30
	s_waitcnt lgkmcnt(0)
	v_add_f32_e32 v62, v30, v31
	ds_read_b128 v[30:33], v83 offset:6656
	ds_bpermute_b32 v63, v80, v62
	s_waitcnt lgkmcnt(1)
	v_mul_f32_e32 v31, v17, v31
	v_fmac_f32_e32 v31, v16, v30
	v_fmac_f32_e32 v31, v18, v32
	v_fmac_f32_e32 v31, v19, v33
	v_add_f32_e32 v34, 0, v31
	ds_read_b128 v[30:33], v83 offset:6784
	s_waitcnt lgkmcnt(0)
	v_mul_f32_e32 v31, v13, v31
	v_fmac_f32_e32 v31, v12, v30
	v_fmac_f32_e32 v31, v14, v32
	v_fmac_f32_e32 v31, v15, v33
	v_add_f32_e32 v34, v34, v31
	ds_read_b128 v[30:33], v83 offset:6912
	s_waitcnt lgkmcnt(0)
	v_mul_f32_e32 v31, v9, v31
	v_fmac_f32_e32 v31, v8, v30
	v_fmac_f32_e32 v31, v10, v32
	v_fmac_f32_e32 v31, v11, v33
	v_add_f32_e32 v34, v34, v31
	ds_read_b128 v[30:33], v83 offset:7040
	s_waitcnt lgkmcnt(0)
	v_mul_f32_e32 v31, v5, v31
	v_fmac_f32_e32 v31, v4, v30
	v_fmac_f32_e32 v31, v6, v32
	v_fmac_f32_e32 v31, v7, v33
	v_add_f32_e32 v30, v34, v31
	ds_bpermute_b32 v31, v82, v30
	s_waitcnt lgkmcnt(0)
	v_add_f32_e32 v30, v30, v31
	ds_bpermute_b32 v31, v81, v30
	s_waitcnt lgkmcnt(0)
	v_add_f32_e32 v65, v30, v31
	ds_read_b128 v[30:33], v83 offset:7168
	ds_bpermute_b32 v66, v80, v65
	s_waitcnt lgkmcnt(1)
	v_mul_f32_e32 v31, v17, v31
	v_fmac_f32_e32 v31, v16, v30
	v_fmac_f32_e32 v31, v18, v32
	v_fmac_f32_e32 v31, v19, v33
	v_add_f32_e32 v34, 0, v31
	ds_read_b128 v[30:33], v83 offset:7296
	s_waitcnt lgkmcnt(0)
	v_mul_f32_e32 v31, v13, v31
	v_fmac_f32_e32 v31, v12, v30
	v_fmac_f32_e32 v31, v14, v32
	v_fmac_f32_e32 v31, v15, v33
	v_add_f32_e32 v34, v34, v31
	ds_read_b128 v[30:33], v83 offset:7424
	s_waitcnt lgkmcnt(0)
	v_mul_f32_e32 v31, v9, v31
	v_fmac_f32_e32 v31, v8, v30
	v_fmac_f32_e32 v31, v10, v32
	v_fmac_f32_e32 v31, v11, v33
	v_add_f32_e32 v34, v34, v31
	ds_read_b128 v[30:33], v83 offset:7552
	s_waitcnt lgkmcnt(0)
	v_mul_f32_e32 v31, v5, v31
	v_fmac_f32_e32 v31, v4, v30
	v_fmac_f32_e32 v31, v6, v32
	v_fmac_f32_e32 v31, v7, v33
	v_add_f32_e32 v30, v34, v31
	ds_bpermute_b32 v31, v82, v30
	s_waitcnt lgkmcnt(0)
	v_add_f32_e32 v30, v30, v31
	ds_bpermute_b32 v31, v81, v30
	s_waitcnt lgkmcnt(0)
	v_add_f32_e32 v67, v30, v31
	ds_read_b128 v[30:33], v83 offset:7680
	ds_bpermute_b32 v68, v80, v67
	s_waitcnt lgkmcnt(1)
	v_mul_f32_e32 v31, v17, v31
	v_fmac_f32_e32 v31, v16, v30
	v_fmac_f32_e32 v31, v18, v32
	v_fmac_f32_e32 v31, v19, v33
	v_add_f32_e32 v34, 0, v31
	ds_read_b128 v[30:33], v83 offset:7808
	s_waitcnt lgkmcnt(0)
	v_mul_f32_e32 v31, v13, v31
	v_fmac_f32_e32 v31, v12, v30
	v_fmac_f32_e32 v31, v14, v32
	v_fmac_f32_e32 v31, v15, v33
	v_add_f32_e32 v34, v34, v31
	ds_read_b128 v[30:33], v83 offset:7936
	s_waitcnt lgkmcnt(0)
	v_mul_f32_e32 v31, v9, v31
	v_fmac_f32_e32 v31, v8, v30
	v_fmac_f32_e32 v31, v10, v32
	v_fmac_f32_e32 v31, v11, v33
	v_add_f32_e32 v34, v34, v31
	ds_read_b128 v[30:33], v83 offset:8064
	s_waitcnt lgkmcnt(0)
	v_mul_f32_e32 v31, v5, v31
	v_fmac_f32_e32 v31, v4, v30
	v_fmac_f32_e32 v31, v6, v32
	v_fmac_f32_e32 v31, v7, v33
	v_add_f32_e32 v30, v34, v31
	ds_bpermute_b32 v31, v82, v30
	v_mov_b32_e32 v82, 0
	s_waitcnt lgkmcnt(0)
	v_add_f32_e32 v30, v30, v31
	ds_bpermute_b32 v31, v81, v30
	v_mov_b32_e32 v81, 0
	s_waitcnt lgkmcnt(0)
	v_add_f32_e32 v71, v30, v31
	v_cndmask_b32_e64 v30, 0, v55, s[4:5]
	v_cndmask_b32_e64 v30, v30, v54, s[6:7]
	v_cndmask_b32_e64 v30, v30, v53, s[8:9]
	v_cndmask_b32_e64 v30, v30, v52, s[10:11]
	v_cndmask_b32_e64 v30, v30, v43, s[12:13]
	v_cndmask_b32_e64 v30, v30, v42, s[14:15]
	v_cndmask_b32_e64 v30, v30, v40, s[16:17]
	ds_bpermute_b32 v72, v80, v71
	v_cndmask_b32_e64 v70, v30, v41, s[18:19]
	ds_read2st64_b32 v[30:31], v74 offset0:47 offset1:63
	ds_read_b32 v80, v79 offset:40960
	s_and_saveexec_b64 s[40:41], s[22:23]
	s_cbranch_execz .LBB0_696
	v_sub_f32_e32 v32, v70, v54
	v_mul_f32_e32 v32, 0x3fb8aa3b, v32
	ds_read_b32 v33, v79 offset:40964
	v_exp_f32_e32 v32, v32
	s_waitcnt lgkmcnt(0)
	v_mul_f32_e32 v32, v32, v33
	v_mul_f32_e32 v32, v25, v32
	v_mul_f32_e32 v82, v31, v32

; __device__ __forceinline__ unsigned pack2(float lo, float hi) { unsigned r; asm("v_cvt_pk_bf16_f32 %0, %1, %2" : "=v"(r) : "v"(lo), "v"(hi)); return r; }
; __device__ __forceinline__ float bf2f(bf16_t h) { return __uint_as_float((unsigned)h << 16); }
; __device__ __forceinline__ float silu_f(float x) { return x * sigm_f(x); }
; __device__ __forceinline__ void sample_ssd(const Params& p, unsigned char* smem, int job) {
;     ...
;         float ycs = 0.f, ct = 0.f;
; #pragma unroll
;         for (int t = 0; t < 8; ++t) { ycs = (nq == t) ? cs[t] : ycs; ct = (nq == t) ? cum[t] : ct; }
;         float y = __expf(ct) * ycs, xt = 0.f;
; #pragma unroll
;         for (int s = 0; s < 8; ++s) {
;             const float xs = xall[s * 1024 + hh * 64 + pp];
;             const float term = (s <= nq) ? G[nq * 8 + s] * __expf(ct - cum[s]) * dtv[s] * xs : 0.f;
;             y += term; xt = (s == nq) ? xs : xt;
;         }
;         y += D_h * xt;
;         const float z = bf2f(U[(size_t)(rowb + nq) * N1P + UC_Z + h * 64 + pp]);
;         y *= silu_f(z);
;         { const unsigned pk = pack2(y, 0.f); MIX[(size_t)(rowb + nq) * MIXW + h * 64 + pp] = (bf16_t)(pk & 0xffffu); }
;         float sq = y * y; sq += __shfl_xor(sq, 8); sq += __shfl_xor(sq, 16); sq += __shfl_xor(sq, 32);
;         if (lane < 8) ssqp[(hh * 8 + wid) * 8 + lane] = sq;
.LBB0_708:
	s_or_b64 exec, exec, s[20:21]
	v_add_f32_e32 v29, v29, v35
	v_add_f32_e32 v56, v56, v57
	v_cndmask_b32_e64 v29, 0, v29, s[4:5]
	v_add_f32_e32 v57, v58, v59
	v_cndmask_b32_e64 v29, v29, v56, s[6:7]
	v_add_f32_e32 v58, v60, v61
	v_cndmask_b32_e64 v29, v29, v57, s[8:9]
	v_add_f32_e32 v59, v62, v63
	v_cndmask_b32_e64 v29, v29, v58, s[10:11]
	v_mul_f32_e32 v35, 0x3fb8aa3b, v70
	v_add_f32_e32 v60, v65, v66
	v_cndmask_b32_e64 v29, v29, v59, s[12:13]
	v_exp_f32_e32 v35, v35
	v_add_f32_e32 v61, v67, v68
	v_cndmask_b32_e64 v29, v29, v60, s[14:15]
	v_add_f32_e32 v62, v71, v72
	v_cndmask_b32_e64 v29, v29, v61, s[16:17]
	v_cndmask_b32_e64 v29, v29, v62, s[18:19]
	v_mul_f32_e32 v29, v35, v29
	v_sub_f32_e32 v35, v70, v55
	v_mul_f32_e32 v35, 0x3fb8aa3b, v35
	v_exp_f32_e32 v35, v35
	v_mov_b64_e32 v[56:57], s[2:3]
	s_or_b32 s6, s44, 15
	v_mad_i64_i32 v[56:57], s[4:5], v46, s45, v[56:57]
	v_mul_f32_e32 v35, v35, v80
	v_mul_f32_e32 v35, v24, v35
	v_fmac_f32_e32 v29, v30, v35
	v_add_f32_e32 v29, v29, v82
	v_add_f32_e32 v29, v29, v83
	v_add_f32_e32 v29, v29, v81
	v_add_f32_e32 v29, v29, v85
	v_add_f32_e32 v29, v29, v84
	v_lshl_add_u64 v[56:57], v[56:57], 0, v[50:51]
	v_lshlrev_b64 v[58:59], 13, v[46:47]
	s_lshl_b32 s96, s6, 7
	v_add_f32_e32 v29, v29, v86
	v_lshl_add_u64 v[58:59], s[72:73], 0, v[58:59]
	v_lshl_add_u64 v[56:57], v[56:57], 0, s[96:97]
	v_lshl_add_u64 v[50:51], v[58:59], 0, v[50:51]
	v_add_f32_e32 v58, v29, v69
	v_mov_b32_e32 v29, v118
	s_nop 0
	v_lshlrev_b32_e32 v59, 16, v29
	v_max_f32_e64 v29, -v59, -v59
	v_min_f32_e32 v29, 0x42a00000, v29
	v_mul_f32_e32 v29, 0x3fb8aa3b, v29
	v_exp_f32_e32 v29, v29
	s_nop 0
	v_add_f32_e32 v35, 1.0, v29
	v_rcp_f32_e32 v29, v35
	s_nop 0
	v_fma_f32 v35, -v35, v29, 2.0
	v_pk_fma_f32 v[56:57], v[28:29], v[34:35], v[58:59]
	v_mul_f32_e32 v28, v29, v35
	v_mul_f32_e32 v28, v28, v59
	v_mul_f32_e32 v34, v56, v28
	v_lshl_add_u64 v[28:29], v[50:51], 0, s[96:97]
	v_cvt_pk_bf16_f32 v35, v34, v149
	global_store_short v[28:29], v35, off
	v_mul_f32_e32 v28, v34, v34
	ds_bpermute_b32 v28, v77, v28
	s_waitcnt lgkmcnt(0)
	v_fmac_f32_e32 v28, v34, v34
	ds_bpermute_b32 v29, v78, v28
	s_waitcnt lgkmcnt(0)
	v_add_f32_e32 v28, v28, v29
	ds_bpermute_b32 v29, v76, v28
	s_and_saveexec_b64 s[4:5], s[0:1]
	s_cbranch_execz .LBB0_710
	v_and_b32_e32 v30, 0x3ffffff8, v44
	v_lshlrev_b32_e32 v30, 2, v30
	v_add3_u32 v30, 0, v30, v75
	s_waitcnt lgkmcnt(0)
	v_add_f32_e32 v28, v28, v29
	ds_write_b32 v30, v28 offset:45568
	ds_read2st64_b32 v[30:31], v74 offset0:47 offset1:63
	ds_read2st64_b32 v[32:33], v74 offset0:79 offset1:95
	ds_read2st64_b32 v[36:37], v74 offset0:111 offset1:127
	ds_read2st64_b32 v[38:39], v74 offset0:143 offset1:159
